# P3 attention PV: counted lgkmcnt waits per MFMA instead of lgkmcnt(0) per group (on top of the rescheduled halves)
# baseline (speedup 1.0000x reference)
.LBB0_433:
	ds_read_b128 v[64:67], v166 offset:49152
	ds_read_b128 v[68:71], v166 offset:57344
	ds_read_b128 v[176:179], v167 offset:49152
	ds_read_b128 v[198:201], v167 offset:57344
	ds_read_b128 v[202:205], v168 offset:49152
	ds_read_b128 v[210:213], v168 offset:57344
	v_exp_f32_e32 v142, v142
	v_exp_f32_e32 v143, v143
	s_waitcnt lgkmcnt(5)
	v_mfma_f32_32x32x16_bf16 v[80:95], v[64:67], v[124:127], 0
	v_exp_f32_e32 v180, v140
	v_exp_f32_e32 v181, v141
	v_exp_f32_e32 v206, v138
	v_exp_f32_e32 v207, v135
	v_exp_f32_e32 v148, v148
	v_exp_f32_e32 v149, v149
	v_exp_f32_e32 v209, v146
	s_waitcnt lgkmcnt(4)
	v_mfma_f32_32x32x16_bf16 v[64:79], v[68:71], v[124:127], 0
	v_cvt_pk_bf16_f32 v135, v192, v193
	v_cvt_pk_bf16_f32 v138, v182, v183
	v_cvt_pk_bf16_f32 v140, v185, v187
	v_cvt_pk_bf16_f32 v141, v188, v189
	s_nop 0
	s_waitcnt lgkmcnt(3)
	v_mfma_f32_32x32x16_bf16 v[80:95], v[176:179], v[120:123], v[80:95]
	ds_read_b128 v[176:179], v169 offset:49152
	ds_read_b128 v[214:217], v169 offset:57344
	ds_read_b128 v[218:221], v170 offset:49152
	ds_read_b128 v[222:225], v170 offset:57344
	ds_read_b128 v[226:229], v171 offset:49152
	ds_read_b128 v[230:233], v171 offset:57344
	ds_read_b128 v[234:237], v172 offset:49152
	ds_read_b128 v[238:241], v172 offset:57344
	s_waitcnt lgkmcnt(10)
	v_mfma_f32_32x32x16_bf16 v[64:79], v[198:201], v[120:123], v[64:79]
	ds_read_b128 v[198:201], v173 offset:49152
	ds_read_b128 v[242:245], v173 offset:57344
	s_waitcnt lgkmcnt(11)
	v_mfma_f32_32x32x16_bf16 v[80:95], v[202:205], v[112:115], v[80:95]
	v_exp_f32_e32 v205, v134
	v_add_f32_e32 v134, v191, v190
	v_add_f32_e32 v134, v192, v134
	v_add_f32_e32 v134, v193, v134
	v_add_f32_e32 v134, v194, v134
	v_add_f32_e32 v134, v196, v134
	s_waitcnt lgkmcnt(10)
	v_mfma_f32_32x32x16_bf16 v[64:79], v[210:213], v[112:115], v[64:79]
	v_add_f32_e32 v134, v195, v134
	v_add_f32_e32 v134, v197, v134
	v_add_f32_e32 v134, v182, v134
	v_add_f32_e32 v134, v183, v134
	v_add_f32_e32 v134, v184, v134
	v_add_f32_e32 v134, v186, v134
	v_add_f32_e32 v134, v185, v134
	s_waitcnt lgkmcnt(9)
	v_mfma_f32_32x32x16_bf16 v[80:95], v[176:179], v[116:119], v[80:95]
	v_add_f32_e32 v134, v187, v134
	v_add_f32_e32 v134, v188, v134
	v_add_f32_e32 v134, v189, v134
	v_add_f32_e32 v134, v142, v134
	v_exp_f32_e32 v202, v139
	v_add_f32_e32 v134, v143, v134
	v_exp_f32_e32 v203, v136
	s_waitcnt lgkmcnt(8)
	v_mfma_f32_32x32x16_bf16 v[64:79], v[214:217], v[116:119], v[64:79]
	v_add_f32_e32 v134, v180, v134
	v_exp_f32_e32 v204, v137
	v_add_f32_e32 v134, v181, v134
	v_add_f32_e32 v134, v206, v134
	v_add_f32_e32 v134, v202, v134
	v_add_f32_e32 v134, v203, v134
	v_add_f32_e32 v134, v204, v134
	s_waitcnt lgkmcnt(7)
	v_mfma_f32_32x32x16_bf16 v[80:95], v[218:221], v[108:111], v[80:95]
	v_add_f32_e32 v134, v205, v134
	v_exp_f32_e32 v210, v147
	v_add_f32_e32 v134, v207, v134
	v_exp_f32_e32 v211, v144
	v_add_f32_e32 v134, v148, v134
	v_exp_f32_e32 v212, v145
	v_add_f32_e32 v134, v149, v134
	s_waitcnt lgkmcnt(6)
	v_mfma_f32_32x32x16_bf16 v[64:79], v[222:225], v[108:111], v[64:79]
	v_add_f32_e32 v134, v209, v134
	v_add_f32_e32 v134, v210, v134
	v_add_f32_e32 v134, v211, v134
	v_add_f32_e32 v176, v212, v134
	v_cvt_pk_bf16_f32 v134, v190, v191
	v_cvt_pk_bf16_f32 v136, v194, v196
	s_waitcnt lgkmcnt(5)
	v_mfma_f32_32x32x16_bf16 v[80:95], v[226:229], v[104:107], v[80:95]
	v_cvt_pk_bf16_f32 v137, v195, v197
	v_cvt_pk_bf16_f32 v139, v184, v186
	v_cvt_pk_bf16_f32 v142, v142, v143
	s_waitcnt lgkmcnt(4)
	v_mfma_f32_32x32x16_bf16 v[64:79], v[230:233], v[104:107], v[64:79]
	v_cvt_pk_bf16_f32 v143, v180, v181
	v_cvt_pk_bf16_f32 v144, v206, v202
	v_cvt_pk_bf16_f32 v145, v203, v204
	v_cvt_pk_bf16_f32 v146, v205, v207
	v_cvt_pk_bf16_f32 v147, v148, v149
	v_cvt_pk_bf16_f32 v148, v209, v210
	v_cvt_pk_bf16_f32 v149, v211, v212
	s_waitcnt lgkmcnt(3)
	v_mfma_f32_32x32x16_bf16 v[80:95], v[234:237], v[100:103], v[80:95]
	s_waitcnt lgkmcnt(2)
	v_mfma_f32_32x32x16_bf16 v[64:79], v[238:241], v[100:103], v[64:79]
	s_waitcnt lgkmcnt(1)
	v_mfma_f32_32x32x16_bf16 v[80:95], v[198:201], v[96:99], v[80:95]
	s_waitcnt lgkmcnt(0)
	v_mfma_f32_32x32x16_bf16 v[64:79], v[242:245], v[96:99], v[64:79]
	global_load_dwordx4 v[218:221], v132, s[28:29]
	global_load_dwordx4 v[222:225], v133, s[28:29]
	global_load_dwordx4 v[226:229], v132, s[30:31]
	global_load_dwordx4 v[230:233], v133, s[30:31]
	s_add_u32 s28, s28, 0x8000
	s_addc_u32 s29, s29, 0
	s_add_u32 s30, s30, 0x8000
	s_addc_u32 s31, s31, 0
	ds_read_b64_tr_b16 v[196:197], v161 offset:0
	ds_read_b64_tr_b16 v[198:199], v161 offset:0x800
	ds_read_b64_tr_b16 v[200:201], v161 offset:0x1000
	ds_read_b64_tr_b16 v[202:203], v161 offset:0x1800
	ds_read_b64_tr_b16 v[204:205], v161 offset:0x2000
	ds_read_b64_tr_b16 v[206:207], v161 offset:0x2800
	ds_read_b64_tr_b16 v[210:211], v161 offset:0x3000
	ds_read_b64_tr_b16 v[212:213], v161 offset:0x3800
	s_nop 0
	s_waitcnt lgkmcnt(6)
	v_mfma_f32_32x32x16_bf16 v[0:15], v[134:137], v[196:199], v[0:15]
	ds_read_b64_tr_b16 v[196:197], v161 offset:0x200
	ds_read_b64_tr_b16 v[198:199], v161 offset:0xa00
	v_max_f32_e32 v234, v80, v81
	v_max3_f32 v234, v234, v82, v83
	v_max3_f32 v234, v234, v84, v85
	v_max3_f32 v234, v234, v86, v87
	v_max3_f32 v234, v234, v88, v89
	s_waitcnt lgkmcnt(6)
	v_mfma_f32_32x32x16_bf16 v[0:15], v[138:141], v[200:203], v[0:15]
	ds_read_b64_tr_b16 v[200:201], v161 offset:0x1200
	ds_read_b64_tr_b16 v[202:203], v161 offset:0x1a00
	v_max3_f32 v234, v234, v90, v91
	v_max3_f32 v234, v234, v92, v93
	v_max3_f32 v234, v234, v94, v95
	v_max3_f32 v234, v234, v64, v65
	v_max3_f32 v234, v234, v66, v67
	s_waitcnt lgkmcnt(6)
	v_mfma_f32_32x32x16_bf16 v[0:15], v[142:145], v[204:207], v[0:15]
	ds_read_b64_tr_b16 v[204:205], v161 offset:0x2200
	ds_read_b64_tr_b16 v[206:207], v161 offset:0x2a00
	ds_read_b64_tr_b16 v[214:215], v161 offset:0x3200
	ds_read_b64_tr_b16 v[216:217], v161 offset:0x3a00
	v_max3_f32 v234, v234, v68, v69
	v_max3_f32 v234, v234, v70, v71
	v_max3_f32 v234, v234, v72, v73
	v_max3_f32 v234, v234, v74, v75
	v_max3_f32 v234, v234, v76, v77
	s_waitcnt lgkmcnt(8)
	v_mfma_f32_32x32x16_bf16 v[0:15], v[146:149], v[210:213], v[0:15]
	v_max3_f32 v234, v234, v78, v79
	v_mov_b32_e32 v235, v234
	s_waitcnt lgkmcnt(6)
	v_mfma_f32_32x32x16_bf16 v[48:63], v[134:137], v[196:199], v[48:63]
	ds_read_b64_tr_b16 v[196:197], v161 offset:0x400
	ds_read_b64_tr_b16 v[198:199], v161 offset:0xc00
	v_permlane32_swap_b32_e32 v234, v235
	v_max_f32_e32 v234, v234, v235
	s_waitcnt lgkmcnt(6)
	v_mfma_f32_32x32x16_bf16 v[48:63], v[138:141], v[200:203], v[48:63]
	ds_read_b64_tr_b16 v[200:201], v161 offset:0x1400
	ds_read_b64_tr_b16 v[202:203], v161 offset:0x1c00
	v_sub_f32_e32 v235, v234, v175
	v_max_f32_e32 v234, v175, v234
	v_sub_f32_e32 v236, v175, v234
	v_mul_f32_e32 v236, 0x3e0293ee, v236
	s_waitcnt lgkmcnt(6)
	v_mfma_f32_32x32x16_bf16 v[48:63], v[142:145], v[204:207], v[48:63]
	ds_read_b64_tr_b16 v[204:205], v161 offset:0x2400
	ds_read_b64_tr_b16 v[206:207], v161 offset:0x2c00
	ds_read_b64_tr_b16 v[210:211], v161 offset:0x3400
	ds_read_b64_tr_b16 v[212:213], v161 offset:0x3c00
	v_exp_f32_e32 v236, v236
	v_cmp_ge_f32_e32 vcc, s15, v235
	s_cmp_eq_u64 vcc, exec
	s_cselect_b64 s[8:9], -1, 0
	s_waitcnt lgkmcnt(8)
	v_mfma_f32_32x32x16_bf16 v[48:63], v[146:149], v[214:217], v[48:63]
	v_cndmask_b32_e64 v179, v236, 1.0, s[8:9]
	v_cndmask_b32_e64 v234, v234, v175, s[8:9]
	v_mul_f32_e32 v238, 0xbe0293ee, v234
	v_pk_fma_f32 v[88:89], v[88:89], s[14:15], v[238:239] op_sel_hi:[1,0,0]
	v_pk_fma_f32 v[80:81], v[80:81], s[14:15], v[238:239] op_sel_hi:[1,0,0]
	s_waitcnt lgkmcnt(6)
	v_mfma_f32_32x32x16_bf16 v[32:47], v[134:137], v[196:199], v[32:47]
	ds_read_b64_tr_b16 v[196:197], v161 offset:0x600
	ds_read_b64_tr_b16 v[198:199], v161 offset:0xe00
	v_pk_fma_f32 v[82:83], v[82:83], s[14:15], v[238:239] op_sel_hi:[1,0,0]
	v_pk_fma_f32 v[84:85], v[84:85], s[14:15], v[238:239] op_sel_hi:[1,0,0]
	v_pk_fma_f32 v[86:87], v[86:87], s[14:15], v[238:239] op_sel_hi:[1,0,0]
	v_pk_fma_f32 v[90:91], v[90:91], s[14:15], v[238:239] op_sel_hi:[1,0,0]
	s_waitcnt lgkmcnt(6)
	v_mfma_f32_32x32x16_bf16 v[32:47], v[138:141], v[200:203], v[32:47]
	ds_read_b64_tr_b16 v[200:201], v161 offset:0x1600
	ds_read_b64_tr_b16 v[202:203], v161 offset:0x1e00
	v_pk_fma_f32 v[92:93], v[92:93], s[14:15], v[238:239] op_sel_hi:[1,0,0]
	v_pk_fma_f32 v[94:95], v[94:95], s[14:15], v[238:239] op_sel_hi:[1,0,0]
	v_pk_fma_f32 v[188:189], v[64:65], s[14:15], v[238:239] op_sel_hi:[1,0,0]
	v_pk_fma_f32 v[190:191], v[66:67], s[14:15], v[238:239] op_sel_hi:[1,0,0]
	s_waitcnt lgkmcnt(6)
	v_mfma_f32_32x32x16_bf16 v[32:47], v[142:145], v[204:207], v[32:47]
	ds_read_b64_tr_b16 v[204:205], v161 offset:0x2600
	ds_read_b64_tr_b16 v[206:207], v161 offset:0x2e00
	ds_read_b64_tr_b16 v[214:215], v161 offset:0x3600
	ds_read_b64_tr_b16 v[216:217], v161 offset:0x3e00
	v_pk_fma_f32 v[182:183], v[70:71], s[14:15], v[238:239] op_sel_hi:[1,0,0]
	v_pk_fma_f32 v[184:185], v[72:73], s[14:15], v[238:239] op_sel_hi:[1,0,0]
	v_pk_fma_f32 v[186:187], v[74:75], s[14:15], v[238:239] op_sel_hi:[1,0,0]
	s_waitcnt lgkmcnt(8)
	v_mfma_f32_32x32x16_bf16 v[32:47], v[146:149], v[210:213], v[32:47]
	v_fmamk_f32 v192, v68, 0x3e0293ee, v238
	v_fmamk_f32 v181, v69, 0x3e0293ee, v238
	v_fmamk_f32 v180, v76, 0x3e0293ee, v238
	s_waitcnt lgkmcnt(6)
	v_mfma_f32_32x32x16_bf16 v[16:31], v[134:137], v[196:199], v[16:31]
	v_fmamk_f32 v193, v77, 0x3e0293ee, v238
	v_fmamk_f32 v194, v78, 0x3e0293ee, v238
	v_fmamk_f32 v177, v79, 0x3e0293ee, v238
	v_mov_b32_e32 v134, v234
	v_exp_f32_e32 v135, v88
	v_exp_f32_e32 v136, v89
	v_exp_f32_e32 v137, v90
	s_waitcnt lgkmcnt(4)
	v_mfma_f32_32x32x16_bf16 v[16:31], v[138:141], v[200:203], v[16:31]
	v_exp_f32_e32 v139, v91
	v_exp_f32_e32 v138, v92
	v_exp_f32_e32 v140, v93
	v_exp_f32_e32 v141, v94
	s_waitcnt lgkmcnt(2)
	v_mfma_f32_32x32x16_bf16 v[16:31], v[142:145], v[204:207], v[16:31]
	v_exp_f32_e32 v142, v95
	v_exp_f32_e32 v143, v80
	v_exp_f32_e32 v144, v81
	v_exp_f32_e32 v145, v82
	s_waitcnt lgkmcnt(0)
	v_mfma_f32_32x32x16_bf16 v[16:31], v[146:149], v[214:217], v[16:31]
	v_exp_f32_e32 v146, v83
	v_exp_f32_e32 v147, v84
	v_exp_f32_e32 v149, v85
	v_exp_f32_e32 v148, v86
	v_exp_f32_e32 v175, v87
	v_cmp_gt_f32_e32 vcc, 1.0, v179
	s_barrier
	s_waitcnt vmcnt(0)
	ds_write_b128 v164, v[218:221]
	ds_write_b128 v165, v[222:225]
	ds_write_b128 v162, v[226:229] offset:32768
	ds_write_b128 v163, v[230:233] offset:32768
	s_cbranch_vccz .LBB0_437
	s_and_saveexec_b64 s[2:3], s[6:7]
	ds_write_b32 v158, v179 offset:128
	s_or_b64 exec, exec, s[2:3]
	s_waitcnt lgkmcnt(0)
	v_add_u32_e32 v234, v131, v128
	ds_read_b128 v[218:221], v234 offset:224
	ds_read_b128 v[222:225], v234 offset:192
	ds_read_b128 v[226:229], v234 offset:160
	ds_read_b128 v[230:233], v234 offset:128
	s_waitcnt lgkmcnt(3)
	v_pk_mul_f32 v[12:13], v[12:13], v[218:219]
	s_waitcnt lgkmcnt(2)
	v_pk_mul_f32 v[8:9], v[8:9], v[222:223]
	s_waitcnt lgkmcnt(1)
	v_pk_mul_f32 v[4:5], v[4:5], v[226:227]
	v_pk_mul_f32 v[14:15], v[14:15], v[220:221]
	v_pk_mul_f32 v[10:11], v[10:11], v[224:225]
	v_pk_mul_f32 v[6:7], v[6:7], v[228:229]
	s_waitcnt lgkmcnt(0)
	v_pk_mul_f32 v[2:3], v[2:3], v[232:233]
	v_pk_mul_f32 v[0:1], v[0:1], v[230:231]
	v_pk_mul_f32 v[60:61], v[60:61], v[218:219]
	v_pk_mul_f32 v[56:57], v[56:57], v[222:223]
	v_pk_mul_f32 v[52:53], v[52:53], v[226:227]
	v_pk_mul_f32 v[62:63], v[62:63], v[220:221]
	v_pk_mul_f32 v[58:59], v[58:59], v[224:225]
	v_pk_mul_f32 v[54:55], v[54:55], v[228:229]
	v_pk_mul_f32 v[50:51], v[50:51], v[232:233]
	v_pk_mul_f32 v[48:49], v[48:49], v[230:231]
	v_pk_mul_f32 v[44:45], v[44:45], v[218:219]
	v_pk_mul_f32 v[40:41], v[40:41], v[222:223]
	v_pk_mul_f32 v[36:37], v[36:37], v[226:227]
	v_pk_mul_f32 v[46:47], v[46:47], v[220:221]
	v_pk_mul_f32 v[42:43], v[42:43], v[224:225]
	v_pk_mul_f32 v[38:39], v[38:39], v[228:229]
	v_pk_mul_f32 v[34:35], v[34:35], v[232:233]
	v_pk_mul_f32 v[32:33], v[32:33], v[230:231]
	v_pk_mul_f32 v[28:29], v[28:29], v[218:219]
	v_pk_mul_f32 v[24:25], v[24:25], v[222:223]
	v_pk_mul_f32 v[20:21], v[20:21], v[226:227]
	v_pk_mul_f32 v[30:31], v[30:31], v[220:221]
	v_pk_mul_f32 v[26:27], v[26:27], v[224:225]
	v_pk_mul_f32 v[22:23], v[22:23], v[228:229]
	v_pk_mul_f32 v[18:19], v[18:19], v[232:233]
	v_pk_mul_f32 v[16:17], v[16:17], v[230:231]
.LBB0_437:
	s_waitcnt lgkmcnt(0)
	s_barrier
	ds_read_b128 v[64:67], v166 offset:32768
	ds_read_b128 v[68:71], v166 offset:40960
	ds_read_b128 v[196:199], v167 offset:32768
	ds_read_b128 v[200:203], v167 offset:40960
	ds_read_b128 v[204:207], v168 offset:32768
	ds_read_b128 v[210:213], v168 offset:40960
	v_exp_f32_e32 v188, v188
	v_exp_f32_e32 v189, v189
	s_waitcnt lgkmcnt(5)
	v_mfma_f32_32x32x16_bf16 v[80:95], v[64:67], v[124:127], 0
	v_exp_f32_e32 v190, v190
	v_exp_f32_e32 v191, v191
	v_exp_f32_e32 v192, v192
	v_exp_f32_e32 v195, v181
	v_exp_f32_e32 v182, v182
	v_exp_f32_e32 v183, v183
	v_exp_f32_e32 v184, v184
	s_waitcnt lgkmcnt(4)
	v_mfma_f32_32x32x16_bf16 v[64:79], v[68:71], v[124:127], 0
	v_exp_f32_e32 v185, v185
	v_exp_f32_e32 v186, v186
	v_exp_f32_e32 v187, v187
	v_exp_f32_e32 v193, v193
	v_exp_f32_e32 v194, v194
	v_exp_f32_e32 v177, v177
	s_waitcnt lgkmcnt(3)
	v_mfma_f32_32x32x16_bf16 v[80:95], v[196:199], v[120:123], v[80:95]
	ds_read_b128 v[196:199], v169 offset:32768
	ds_read_b128 v[214:217], v169 offset:40960
	ds_read_b128 v[218:221], v170 offset:32768
	ds_read_b128 v[222:225], v170 offset:40960
	ds_read_b128 v[226:229], v171 offset:32768
	ds_read_b128 v[230:233], v171 offset:40960
	ds_read_b128 v[234:237], v172 offset:32768
	ds_read_b128 v[238:241], v172 offset:40960
	s_waitcnt lgkmcnt(10)
	v_mfma_f32_32x32x16_bf16 v[64:79], v[200:203], v[120:123], v[64:79]
	ds_read_b128 v[200:203], v173 offset:32768
	ds_read_b128 v[242:245], v173 offset:40960
	s_waitcnt lgkmcnt(11)
	v_mfma_f32_32x32x16_bf16 v[80:95], v[204:207], v[112:115], v[80:95]
	v_exp_f32_e32 v204, v180
	v_add_f32_e32 v180, v144, v143
	v_add_f32_e32 v180, v145, v180
	v_add_f32_e32 v180, v146, v180
	v_add_f32_e32 v180, v147, v180
	v_add_f32_e32 v180, v149, v180
	s_waitcnt lgkmcnt(10)
	v_mfma_f32_32x32x16_bf16 v[64:79], v[210:213], v[112:115], v[64:79]
	v_add_f32_e32 v180, v148, v180
	v_add_f32_e32 v180, v175, v180
	v_add_f32_e32 v180, v135, v180
	v_add_f32_e32 v180, v136, v180
	v_add_f32_e32 v180, v137, v180
	v_add_f32_e32 v180, v139, v180
	v_add_f32_e32 v180, v138, v180
	s_waitcnt lgkmcnt(9)
	v_mfma_f32_32x32x16_bf16 v[80:95], v[196:199], v[116:119], v[80:95]
	v_add_f32_e32 v180, v140, v180
	v_add_f32_e32 v180, v141, v180
	v_add_f32_e32 v180, v142, v180
	v_add_f32_e32 v180, v188, v180
	v_add_f32_e32 v180, v189, v180
	v_add_f32_e32 v180, v190, v180
	v_add_f32_e32 v180, v191, v180
	s_waitcnt lgkmcnt(8)
	v_mfma_f32_32x32x16_bf16 v[64:79], v[214:217], v[116:119], v[64:79]
	v_add_f32_e32 v180, v192, v180
	v_add_f32_e32 v180, v195, v180
	v_add_f32_e32 v180, v182, v180
	v_add_f32_e32 v180, v183, v180
	v_add_f32_e32 v180, v184, v180
	v_add_f32_e32 v180, v185, v180
	v_add_f32_e32 v180, v186, v180
	s_waitcnt lgkmcnt(7)
	v_mfma_f32_32x32x16_bf16 v[80:95], v[218:221], v[108:111], v[80:95]
	v_add_f32_e32 v180, v187, v180
	v_add_f32_e32 v180, v204, v180
	v_add_f32_e32 v180, v193, v180
	v_add_f32_e32 v180, v194, v180
	v_add_f32_e32 v180, v177, v180
	s_waitcnt lgkmcnt(6)
	v_mfma_f32_32x32x16_bf16 v[64:79], v[222:225], v[108:111], v[64:79]
	v_cvt_pk_bf16_f32 v144, v143, v144
	v_cvt_pk_bf16_f32 v145, v145, v146
	v_cvt_pk_bf16_f32 v146, v147, v149
	v_cvt_pk_bf16_f32 v147, v148, v175
	v_cvt_pk_bf16_f32 v136, v135, v136
	v_cvt_pk_bf16_f32 v137, v137, v139
	v_cvt_pk_bf16_f32 v138, v138, v140
	s_waitcnt lgkmcnt(5)
	v_mfma_f32_32x32x16_bf16 v[80:95], v[226:229], v[104:107], v[80:95]
	v_cvt_pk_bf16_f32 v139, v141, v142
	v_cvt_pk_bf16_f32 v140, v188, v189
	v_cvt_pk_bf16_f32 v141, v190, v191
	v_cvt_pk_bf16_f32 v142, v192, v195
	v_cvt_pk_bf16_f32 v143, v182, v183
	v_cvt_pk_bf16_f32 v182, v184, v185
	v_cvt_pk_bf16_f32 v183, v186, v187
	s_waitcnt lgkmcnt(4)
	v_mfma_f32_32x32x16_bf16 v[64:79], v[230:233], v[104:107], v[64:79]
	v_cvt_pk_bf16_f32 v184, v204, v193
	v_cvt_pk_bf16_f32 v185, v194, v177
	s_waitcnt lgkmcnt(3)
	v_mfma_f32_32x32x16_bf16 v[80:95], v[234:237], v[100:103], v[80:95]
	s_waitcnt lgkmcnt(2)
	v_mfma_f32_32x32x16_bf16 v[64:79], v[238:241], v[100:103], v[64:79]
	s_waitcnt lgkmcnt(1)
	v_mfma_f32_32x32x16_bf16 v[80:95], v[200:203], v[96:99], v[80:95]
	s_waitcnt lgkmcnt(0)
	v_mfma_f32_32x32x16_bf16 v[64:79], v[242:245], v[96:99], v[64:79]
	global_load_dwordx4 v[226:229], v132, s[28:29]
	global_load_dwordx4 v[230:233], v132, s[30:31]
	global_load_dwordx4 v[234:237], v133, s[28:29]
	global_load_dwordx4 v[238:241], v133, s[30:31]
	s_add_u32 s28, s28, 0x8000
	s_addc_u32 s29, s29, 0
	s_add_u32 s30, s30, 0x8000
	s_addc_u32 s31, s31, 0
	ds_read_b64_tr_b16 v[202:203], v160 offset:0
	ds_read_b64_tr_b16 v[204:205], v160 offset:0x800
	ds_read_b64_tr_b16 v[210:211], v160 offset:0x1000
	ds_read_b64_tr_b16 v[212:213], v160 offset:0x1800
	ds_read_b64_tr_b16 v[214:215], v160 offset:0x2000
	ds_read_b64_tr_b16 v[216:217], v160 offset:0x2800
	ds_read_b64_tr_b16 v[218:219], v160 offset:0x3000
	ds_read_b64_tr_b16 v[220:221], v160 offset:0x3800
	s_nop 0
	s_waitcnt lgkmcnt(6)
	v_mfma_f32_32x32x16_bf16 v[0:15], v[144:147], v[202:205], v[0:15]
	ds_read_b64_tr_b16 v[202:203], v160 offset:0x200
	ds_read_b64_tr_b16 v[204:205], v160 offset:0xa00
	v_max_f32_e32 v242, v80, v81
	v_max3_f32 v242, v242, v82, v83
	v_max3_f32 v242, v242, v84, v85
	v_max3_f32 v242, v242, v86, v87
	v_max3_f32 v242, v242, v88, v89
	s_waitcnt lgkmcnt(6)
	v_mfma_f32_32x32x16_bf16 v[0:15], v[136:139], v[210:213], v[0:15]
	ds_read_b64_tr_b16 v[210:211], v160 offset:0x1200
	ds_read_b64_tr_b16 v[212:213], v160 offset:0x1a00
	v_max3_f32 v242, v242, v90, v91
	v_max3_f32 v242, v242, v92, v93
	v_max3_f32 v242, v242, v94, v95
	v_max3_f32 v242, v242, v64, v65
	v_max3_f32 v242, v242, v66, v67
	s_waitcnt lgkmcnt(6)
	v_mfma_f32_32x32x16_bf16 v[0:15], v[140:143], v[214:217], v[0:15]
	ds_read_b64_tr_b16 v[214:215], v160 offset:0x2200
	ds_read_b64_tr_b16 v[216:217], v160 offset:0x2a00
	ds_read_b64_tr_b16 v[222:223], v160 offset:0x3200
	ds_read_b64_tr_b16 v[224:225], v160 offset:0x3a00
	v_max3_f32 v242, v242, v68, v69
	v_max3_f32 v242, v242, v70, v71
	v_max3_f32 v242, v242, v72, v73
	v_max3_f32 v242, v242, v74, v75
	v_max3_f32 v242, v242, v76, v77
	s_waitcnt lgkmcnt(8)
	v_mfma_f32_32x32x16_bf16 v[0:15], v[182:185], v[218:221], v[0:15]
	v_max3_f32 v242, v242, v78, v79
	v_mov_b32_e32 v243, v242
	s_waitcnt lgkmcnt(6)
	v_mfma_f32_32x32x16_bf16 v[48:63], v[144:147], v[202:205], v[48:63]
	ds_read_b64_tr_b16 v[202:203], v160 offset:0x400
	ds_read_b64_tr_b16 v[204:205], v160 offset:0xc00
	v_permlane32_swap_b32_e32 v242, v243
	v_max_f32_e32 v242, v242, v243
	s_waitcnt lgkmcnt(6)
	v_mfma_f32_32x32x16_bf16 v[48:63], v[136:139], v[210:213], v[48:63]
	ds_read_b64_tr_b16 v[210:211], v160 offset:0x1400
	ds_read_b64_tr_b16 v[212:213], v160 offset:0x1c00
	v_sub_f32_e32 v243, v242, v134
	v_max_f32_e32 v242, v134, v242
	v_sub_f32_e32 v148, v134, v242
	v_mul_f32_e32 v148, 0x3e0293ee, v148
	s_waitcnt lgkmcnt(6)
	v_mfma_f32_32x32x16_bf16 v[48:63], v[140:143], v[214:217], v[48:63]
	ds_read_b64_tr_b16 v[214:215], v160 offset:0x2400
	ds_read_b64_tr_b16 v[216:217], v160 offset:0x2c00
	ds_read_b64_tr_b16 v[218:219], v160 offset:0x3400
	ds_read_b64_tr_b16 v[220:221], v160 offset:0x3c00
	v_exp_f32_e32 v148, v148
	v_cmp_ge_f32_e32 vcc, s15, v243
	s_cmp_eq_u64 vcc, exec
	s_cselect_b64 s[8:9], -1, 0
	s_waitcnt lgkmcnt(8)
	v_mfma_f32_32x32x16_bf16 v[48:63], v[182:185], v[222:225], v[48:63]
	v_cndmask_b32_e64 v177, v148, 1.0, s[8:9]
	v_cndmask_b32_e64 v175, v242, v134, s[8:9]
	v_mul_f32_e32 v244, 0xbe0293ee, v175
	v_pk_fma_f32 v[80:81], v[80:81], s[14:15], v[244:245] op_sel_hi:[1,0,0]
	v_pk_fma_f32 v[82:83], v[82:83], s[14:15], v[244:245] op_sel_hi:[1,0,0]
	s_waitcnt lgkmcnt(6)
	v_mfma_f32_32x32x16_bf16 v[32:47], v[144:147], v[202:205], v[32:47]
	ds_read_b64_tr_b16 v[202:203], v160 offset:0x600
	ds_read_b64_tr_b16 v[204:205], v160 offset:0xe00
	v_pk_fma_f32 v[84:85], v[84:85], s[14:15], v[244:245] op_sel_hi:[1,0,0]
	v_pk_fma_f32 v[86:87], v[86:87], s[14:15], v[244:245] op_sel_hi:[1,0,0]
	v_pk_fma_f32 v[88:89], v[88:89], s[14:15], v[244:245] op_sel_hi:[1,0,0]
	v_pk_fma_f32 v[90:91], v[90:91], s[14:15], v[244:245] op_sel_hi:[1,0,0]
	s_waitcnt lgkmcnt(6)
	v_mfma_f32_32x32x16_bf16 v[32:47], v[136:139], v[210:213], v[32:47]
	ds_read_b64_tr_b16 v[210:211], v160 offset:0x1600
	ds_read_b64_tr_b16 v[212:213], v160 offset:0x1e00
	v_pk_fma_f32 v[92:93], v[92:93], s[14:15], v[244:245] op_sel_hi:[1,0,0]
	v_pk_fma_f32 v[94:95], v[94:95], s[14:15], v[244:245] op_sel_hi:[1,0,0]
	v_pk_fma_f32 v[134:135], v[72:73], s[14:15], v[244:245] op_sel_hi:[1,0,0]
	v_pk_fma_f32 v[148:149], v[74:75], s[14:15], v[244:245] op_sel_hi:[1,0,0]
	s_waitcnt lgkmcnt(6)
	v_mfma_f32_32x32x16_bf16 v[32:47], v[140:143], v[214:217], v[32:47]
	ds_read_b64_tr_b16 v[214:215], v160 offset:0x2600
	ds_read_b64_tr_b16 v[216:217], v160 offset:0x2e00
	ds_read_b64_tr_b16 v[222:223], v160 offset:0x3600
	ds_read_b64_tr_b16 v[224:225], v160 offset:0x3e00
	v_exp_f32_e32 v190, v80
	v_exp_f32_e32 v191, v81
	v_exp_f32_e32 v192, v82
	s_waitcnt lgkmcnt(8)
	v_mfma_f32_32x32x16_bf16 v[32:47], v[182:185], v[218:221], v[32:47]
	v_exp_f32_e32 v193, v83
	v_exp_f32_e32 v194, v84
	v_exp_f32_e32 v196, v85
	s_waitcnt lgkmcnt(6)
	v_mfma_f32_32x32x16_bf16 v[16:31], v[144:147], v[202:205], v[16:31]
	v_pk_fma_f32 v[144:145], v[78:79], s[14:15], v[244:245] op_sel_hi:[1,0,0]
	v_pk_fma_f32 v[146:147], v[76:77], s[14:15], v[244:245] op_sel_hi:[1,0,0]
	v_exp_f32_e32 v195, v86
	v_exp_f32_e32 v197, v87
	s_waitcnt lgkmcnt(4)
	v_mfma_f32_32x32x16_bf16 v[16:31], v[136:139], v[210:213], v[16:31]
	v_pk_fma_f32 v[136:137], v[70:71], s[14:15], v[244:245] op_sel_hi:[1,0,0]
	v_pk_fma_f32 v[138:139], v[68:69], s[14:15], v[244:245] op_sel_hi:[1,0,0]
	v_exp_f32_e32 v186, v91
	v_exp_f32_e32 v187, v93
	s_waitcnt lgkmcnt(2)
	v_mfma_f32_32x32x16_bf16 v[16:31], v[140:143], v[214:217], v[16:31]
	v_pk_fma_f32 v[140:141], v[66:67], s[14:15], v[244:245] op_sel_hi:[1,0,0]
	v_pk_fma_f32 v[142:143], v[64:65], s[14:15], v[244:245] op_sel_hi:[1,0,0]
	v_exp_f32_e32 v188, v94
	v_exp_f32_e32 v189, v95
	s_waitcnt lgkmcnt(0)
	v_mfma_f32_32x32x16_bf16 v[16:31], v[182:185], v[222:225], v[16:31]
	v_exp_f32_e32 v182, v88
	v_exp_f32_e32 v183, v89
	v_exp_f32_e32 v184, v90
	v_exp_f32_e32 v185, v92
	v_cmp_gt_f32_e32 vcc, 1.0, v177
	s_barrier
	s_waitcnt vmcnt(0)
	ds_write_b128 v164, v[226:229] offset:16384
	ds_write_b128 v165, v[234:237] offset:16384
	ds_write_b128 v162, v[230:233] offset:49152
	ds_write_b128 v163, v[238:241] offset:49152
	s_cbranch_vccz .LBB0_441
	s_and_saveexec_b64 s[2:3], s[6:7]
	ds_write_b32 v158, v177 offset:128
	s_or_b64 exec, exec, s[2:3]
	s_waitcnt lgkmcnt(0)
	v_add_u32_e32 v242, v131, v128
	ds_read_b128 v[226:229], v242 offset:224
	ds_read_b128 v[230:233], v242 offset:192
	ds_read_b128 v[234:237], v242 offset:160
	ds_read_b128 v[238:241], v242 offset:128
	s_waitcnt lgkmcnt(3)
	v_pk_mul_f32 v[12:13], v[12:13], v[226:227]
	s_waitcnt lgkmcnt(2)
	v_pk_mul_f32 v[8:9], v[8:9], v[230:231]
	s_waitcnt lgkmcnt(1)
	v_pk_mul_f32 v[4:5], v[4:5], v[234:235]
	v_pk_mul_f32 v[14:15], v[14:15], v[228:229]
	v_pk_mul_f32 v[10:11], v[10:11], v[232:233]
	v_pk_mul_f32 v[6:7], v[6:7], v[236:237]
	s_waitcnt lgkmcnt(0)
	v_pk_mul_f32 v[2:3], v[2:3], v[240:241]
	v_pk_mul_f32 v[0:1], v[0:1], v[238:239]
	v_pk_mul_f32 v[60:61], v[60:61], v[226:227]
	v_pk_mul_f32 v[56:57], v[56:57], v[230:231]
	v_pk_mul_f32 v[52:53], v[52:53], v[234:235]
	v_pk_mul_f32 v[62:63], v[62:63], v[228:229]
	v_pk_mul_f32 v[58:59], v[58:59], v[232:233]
	v_pk_mul_f32 v[54:55], v[54:55], v[236:237]
	v_pk_mul_f32 v[50:51], v[50:51], v[240:241]
	v_pk_mul_f32 v[48:49], v[48:49], v[238:239]
	v_pk_mul_f32 v[44:45], v[44:45], v[226:227]
	v_pk_mul_f32 v[40:41], v[40:41], v[230:231]
	v_pk_mul_f32 v[36:37], v[36:37], v[234:235]
	v_pk_mul_f32 v[46:47], v[46:47], v[228:229]
	v_pk_mul_f32 v[42:43], v[42:43], v[232:233]
	v_pk_mul_f32 v[38:39], v[38:39], v[236:237]
	v_pk_mul_f32 v[34:35], v[34:35], v[240:241]
	v_pk_mul_f32 v[32:33], v[32:33], v[238:239]
	v_pk_mul_f32 v[28:29], v[28:29], v[226:227]
	v_pk_mul_f32 v[24:25], v[24:25], v[230:231]
	v_pk_mul_f32 v[20:21], v[20:21], v[234:235]
	v_pk_mul_f32 v[30:31], v[30:31], v[228:229]
	v_pk_mul_f32 v[26:27], v[26:27], v[232:233]
	v_pk_mul_f32 v[22:23], v[22:23], v[236:237]
	v_pk_mul_f32 v[18:19], v[18:19], v[240:241]
	v_pk_mul_f32 v[16:17], v[16:17], v[238:239]
